# gamma table of the first norm phase built by workgroups 128..157 (four row iterations) instead of 0..29 (five), on top of the previous version
# speedup vs baseline: 1.0057x; 1.0057x over previous
.Lxb0_rel:
.Lxb0_done:
.LBB0_151:
	s_or_b64 exec, exec, s[4:5]
	s_mov_b32 s0, 0
	s_waitcnt lgkmcnt(0)
	s_barrier
	s_load_dwordx2 s[18:19], s[82:83], 0xb0
	v_mbcnt_lo_u32_b32 v0, -1, s0
	s_waitcnt vmcnt(10)
	v_mbcnt_hi_u32_b32 v8, -1, v0
	s_waitcnt lgkmcnt(0)
	s_add_u32 s4, s18, 0x10000
	s_addc_u32 s5, s19, 0
	s_add_i32 s0, s72, s3
	s_add_i32 s94, s0, 0xffff0000
	s_cmp_eq_u32 s74, 0x100
	s_cselect_b32 s0, s94, s0
	v_add_u32_e32 v0, s0, v8
	s_movk_i32 s0, 0x3c00
	v_cmp_gt_u32_e32 vcc, s0, v0
	s_and_saveexec_b64 s[6:7], vcc
	s_cbranch_execz .LBB0_161
	v_ashrrev_i32_e32 v1, 10, v0
	s_mov_b32 s0, 0x66666667
	v_mul_hi_i32 v2, v1, s0
	v_lshrrev_b32_e32 v3, 31, v2
	v_ashrrev_i32_e32 v2, 1, v2
	v_add_u32_e32 v2, v2, v3
	v_lshl_add_u32 v2, v2, 2, v2
	v_sub_u32_e32 v1, v1, v2
	v_add_u32_e32 v2, 0x13ff, v0
	s_movk_i32 s1, 0x27fe
	v_and_b32_e32 v6, 0x3ff, v0
	s_movk_i32 s0, 0x13ff
	v_cmp_lt_u32_e32 vcc, s1, v2
	s_and_saveexec_b64 s[2:3], vcc
	s_xor_b64 s[8:9], exec, s[2:3]
	s_cbranch_execz .LBB0_158
	v_add_u32_e32 v2, 0xffffec00, v0
	v_cmp_lt_u32_e32 vcc, s0, v2
	v_mov_b32_e32 v7, 0
	s_and_saveexec_b64 s[0:1], vcc
	s_xor_b64 s[12:13], exec, s[0:1]
	s_cbranch_execz .LBB0_155
	s_load_dwordx2 s[0:1], s[82:83], 0x38
	v_lshlrev_b32_e32 v6, 2, v6
	v_add_u32_e32 v1, 5, v1
	v_mov_b64_e32 v[4:5], s[4:5]
	s_mov_b64 s[2:3], 0x1000
	s_waitcnt lgkmcnt(0)
	v_lshl_add_u64 v[2:3], s[0:1], 0, v[6:7]
	s_movk_i32 s0, 0x6000
	v_mad_u64_u32 v[4:5], s[0:1], v1, s0, v[4:5]
	v_lshl_add_u64 v[4:5], v[4:5], 0, v[6:7]
	s_mov_b64 s[0:1], 0x4000
	v_lshl_add_u64 v[2:3], v[2:3], 0, s[2:3]
	v_lshl_add_u64 v[4:5], v[4:5], 0, s[0:1]
